# static s_setprio 1 for the scan waves (0-3) during their attention strips
# baseline (speedup 1.0000x reference)
; __global__ void __launch_bounds__(NT, 2) hymba_fwd(Args args) {
;     ...
;     if (IN(5)) {
;         if (tid == 0) MISC[4] = 0u;
;         __syncthreads();
;         if (tid < 256) { const int gid = (bid * 256 + tid) & 65535;
;             const int h = gid >> 14, dd = gid & 127; float run = 0.f;
;             bf16* p = DST + gid; const float* dc = DEC + h * 128 + dd;
;             unsigned v[32]; float dv[32];
; #pragma unroll
;             for (int j = 0; j < 32; ++j) { v[j] = p[(size_t)j * 65536]; dv[j] = dc[j * 512]; }
.LBB0_1036:
	s_or_b64 exec, exec, s[0:1]
	s_movk_i32 s0, 0x100
	v_cmp_gt_u32_e32 vcc, s0, v179
	s_waitcnt vmcnt(0) lgkmcnt(0)
	s_barrier
	s_and_saveexec_b64 s[0:1], vcc
	s_cbranch_execz .LBB0_1039
	v_readlane_b32 s4, v237, 23
	v_readlane_b32 s6, v237, 27
	v_readlane_b32 s7, v237, 28
	v_and_b32_e32 v176, 63, v179
	v_and_b32_e32 v177, 0xc0, v179
	s_lshl_b32 s5, s4, 8
	s_and_b32 s5, s5, 0xff00
	s_lshl_b32 s4, s4, 3
	s_and_b32 s4, s4, 0x600
	v_and_b32_e32 v193, 7, v176
	v_lshlrev_b32_e32 v193, 3, v193
	v_add3_u32 v193, v193, v177, s5
	v_lshlrev_b32_e32 v193, 1, v193
	v_lshrrev_b32_e32 v198, 3, v176
	v_lshl_add_u32 v198, v198, 17, v193
	v_and_b32_e32 v193, 15, v176
	v_lshlrev_b32_e32 v193, 4, v193
	v_and_b32_e32 v199, 64, v179
	v_lshl_add_u32 v193, v199, 2, v193
	v_add_u32_e32 v193, s4, v193
	v_lshrrev_b32_e32 v199, 4, v176
	v_lshl_add_u32 v199, v199, 11, v193
	v_lshrrev_b32_e32 v177, 6, v177
	v_mul_u32_u24_e32 v177, 0x3000, v177
	v_add_u32_e32 v177, 0x10000, v177
	v_lshl_add_u32 v200, v176, 4, v177
	v_lshl_add_u32 v201, v176, 1, v177
	v_lshl_add_u32 v202, v176, 2, v177
	s_mov_b32 s8, s60
	s_mov_b32 s9, s61
	s_mov_b32 s12, s60
	s_mov_b32 s13, s61
	s_movk_i32 s10, 0x7fff
	v_mov_b32_e32 v211, 0
	s_nop 4
	global_load_dwordx4 v[0:3], v198, s[8:9]
	s_add_u32 s8, s8, 0x100000
	s_addc_u32 s9, s9, 0
	global_load_dwordx4 v[4:7], v198, s[8:9]
	s_add_u32 s8, s8, 0x100000
	s_addc_u32 s9, s9, 0
	global_load_dwordx4 v[8:11], v198, s[8:9]
	s_add_u32 s8, s8, 0x100000
	s_addc_u32 s9, s9, 0
	global_load_dwordx4 v[12:15], v198, s[8:9]
	s_add_u32 s8, s8, 0x100000
	s_addc_u32 s9, s9, 0
	global_load_dwordx4 v[64:67], v199, s[6:7]
	s_add_u32 s6, s6, 0x2000
	s_addc_u32 s7, s7, 0
	global_load_dwordx4 v[68:71], v199, s[6:7]
	s_add_u32 s6, s6, 0x2000
	s_addc_u32 s7, s7, 0
	global_load_dwordx4 v[72:75], v199, s[6:7]
	s_add_u32 s6, s6, 0x2000
	s_addc_u32 s7, s7, 0
	global_load_dwordx4 v[76:79], v199, s[6:7]
	s_add_u32 s6, s6, 0x2000
	s_addc_u32 s7, s7, 0
	global_load_dwordx4 v[80:83], v199, s[6:7]
	s_add_u32 s6, s6, 0x2000
	s_addc_u32 s7, s7, 0
	global_load_dwordx4 v[84:87], v199, s[6:7]
	s_add_u32 s6, s6, 0x2000
	s_addc_u32 s7, s7, 0
	global_load_dwordx4 v[88:91], v199, s[6:7]
	s_add_u32 s6, s6, 0x2000
	s_addc_u32 s7, s7, 0
	global_load_dwordx4 v[92:95], v199, s[6:7]
	s_add_u32 s6, s6, 0x2000
	s_addc_u32 s7, s7, 0
	global_load_dwordx4 v[16:19], v198, s[8:9]
	s_add_u32 s8, s8, 0x100000
	s_addc_u32 s9, s9, 0
	global_load_dwordx4 v[20:23], v198, s[8:9]
	s_add_u32 s8, s8, 0x100000
	s_addc_u32 s9, s9, 0
	global_load_dwordx4 v[24:27], v198, s[8:9]
	s_add_u32 s8, s8, 0x100000
	s_addc_u32 s9, s9, 0
	global_load_dwordx4 v[28:31], v198, s[8:9]
	s_add_u32 s8, s8, 0x100000
	s_addc_u32 s9, s9, 0
	global_load_dwordx4 v[96:99], v199, s[6:7]
	s_add_u32 s6, s6, 0x2000
	s_addc_u32 s7, s7, 0
	global_load_dwordx4 v[100:103], v199, s[6:7]
	s_add_u32 s6, s6, 0x2000
	s_addc_u32 s7, s7, 0
	global_load_dwordx4 v[104:107], v199, s[6:7]
	s_add_u32 s6, s6, 0x2000
	s_addc_u32 s7, s7, 0
	global_load_dwordx4 v[108:111], v199, s[6:7]
	s_add_u32 s6, s6, 0x2000
	s_addc_u32 s7, s7, 0
	global_load_dwordx4 v[112:115], v199, s[6:7]
	s_add_u32 s6, s6, 0x2000
	s_addc_u32 s7, s7, 0
	global_load_dwordx4 v[116:119], v199, s[6:7]
	s_add_u32 s6, s6, 0x2000
	s_addc_u32 s7, s7, 0
	global_load_dwordx4 v[120:123], v199, s[6:7]
	s_add_u32 s6, s6, 0x2000
	s_addc_u32 s7, s7, 0
	global_load_dwordx4 v[124:127], v199, s[6:7]
	s_add_u32 s6, s6, 0x2000
	s_addc_u32 s7, s7, 0
	global_load_dwordx4 v[32:35], v198, s[8:9]
	s_add_u32 s8, s8, 0x100000
	s_addc_u32 s9, s9, 0
	global_load_dwordx4 v[36:39], v198, s[8:9]
	s_add_u32 s8, s8, 0x100000
	s_addc_u32 s9, s9, 0
	global_load_dwordx4 v[40:43], v198, s[8:9]
	s_add_u32 s8, s8, 0x100000
	s_addc_u32 s9, s9, 0
	global_load_dwordx4 v[44:47], v198, s[8:9]
	s_add_u32 s8, s8, 0x100000
	s_addc_u32 s9, s9, 0
	global_load_dwordx4 v[128:131], v199, s[6:7]
	s_add_u32 s6, s6, 0x2000
	s_addc_u32 s7, s7, 0
	global_load_dwordx4 v[132:135], v199, s[6:7]
	s_add_u32 s6, s6, 0x2000
	s_addc_u32 s7, s7, 0
	global_load_dwordx4 v[136:139], v199, s[6:7]
	s_add_u32 s6, s6, 0x2000
	s_addc_u32 s7, s7, 0
	global_load_dwordx4 v[140:143], v199, s[6:7]
	s_add_u32 s6, s6, 0x2000
	s_addc_u32 s7, s7, 0
	global_load_dwordx4 v[144:147], v199, s[6:7]
	s_add_u32 s6, s6, 0x2000
	s_addc_u32 s7, s7, 0
	global_load_dwordx4 v[148:151], v199, s[6:7]
	s_add_u32 s6, s6, 0x2000
	s_addc_u32 s7, s7, 0
	global_load_dwordx4 v[152:155], v199, s[6:7]
	s_add_u32 s6, s6, 0x2000
	s_addc_u32 s7, s7, 0
	global_load_dwordx4 v[156:159], v199, s[6:7]
	s_add_u32 s6, s6, 0x2000
	s_addc_u32 s7, s7, 0
	global_load_dwordx4 v[48:51], v198, s[8:9]
	s_add_u32 s8, s8, 0x100000
	s_addc_u32 s9, s9, 0
	global_load_dwordx4 v[52:55], v198, s[8:9]
	s_add_u32 s8, s8, 0x100000
	s_addc_u32 s9, s9, 0
	global_load_dwordx4 v[56:59], v198, s[8:9]
	s_add_u32 s8, s8, 0x100000
	s_addc_u32 s9, s9, 0
	global_load_dwordx4 v[60:63], v198, s[8:9]
	s_add_u32 s8, s8, 0x100000
	s_addc_u32 s9, s9, 0
	global_load_dwordx4 v[160:163], v199, s[6:7]
	s_add_u32 s6, s6, 0x2000
	s_addc_u32 s7, s7, 0
	global_load_dwordx4 v[164:167], v199, s[6:7]
	s_add_u32 s6, s6, 0x2000
	s_addc_u32 s7, s7, 0
	global_load_dwordx4 v[168:171], v199, s[6:7]
	s_add_u32 s6, s6, 0x2000
	s_addc_u32 s7, s7, 0
	global_load_dwordx4 v[172:175], v199, s[6:7]
	s_add_u32 s6, s6, 0x2000
	s_addc_u32 s7, s7, 0
	global_load_dwordx4 v[180:183], v199, s[6:7]
	s_add_u32 s6, s6, 0x2000
	s_addc_u32 s7, s7, 0
	global_load_dwordx4 v[184:187], v199, s[6:7]
	s_add_u32 s6, s6, 0x2000
	s_addc_u32 s7, s7, 0
	global_load_dwordx4 v[188:191], v199, s[6:7]
	s_add_u32 s6, s6, 0x2000
	s_addc_u32 s7, s7, 0
	global_load_dwordx4 v[194:197], v199, s[6:7]
	s_add_u32 s6, s6, 0x2000
	s_addc_u32 s7, s7, 0
	s_waitcnt vmcnt(36)
; __device__ __forceinline__ unsigned f2bf(float f) { unsigned u = __builtin_bit_cast(unsigned, f); return (u + 0x7fffu + ((u >> 16) & 1u)) >> 16; }
; __global__ void __launch_bounds__(NT, 2) hymba_fwd(Args args) {
;     ...
;             for (int cb = 0; cb < 128; cb += 32) {
;                 unsigned vn[32]; float dn[32];
;                 const int nb = cb + 32 < 128 ? cb + 32 : cb;
; #pragma unroll
;                 for (int j = 0; j < 32; ++j) { vn[j] = p[(size_t)(nb + j) * 65536]; dn[j] = dc[(nb + j) * 512]; }
; #pragma unroll
;                 for (int j = 0; j < 32; ++j) { run = dv[j] * run + bf2f((unsigned short)v[j]); v[j] = f2bf(run); }
; #pragma unroll
;                 for (int j = 0; j < 32; ++j) { p[(size_t)(cb + j) * 65536] = (bf16)v[j]; v[j] = vn[j]; dv[j] = dn[j]; }
	ds_write_b128 v200, v[0:3] offset:0
	ds_write_b128 v200, v[4:7] offset:1024
	ds_write_b128 v200, v[8:11] offset:2048
	ds_write_b128 v200, v[12:15] offset:3072
	ds_write_b128 v200, v[64:67] offset:4096
	ds_write_b128 v200, v[68:71] offset:5120
	ds_write_b128 v200, v[72:75] offset:6144
	ds_write_b128 v200, v[76:79] offset:7168
	ds_write_b128 v200, v[80:83] offset:8192
	ds_write_b128 v200, v[84:87] offset:9216
	ds_write_b128 v200, v[88:91] offset:10240
	ds_write_b128 v200, v[92:95] offset:11264
	ds_read_u16 v203, v201 offset:0
	ds_read_b32 v207, v202 offset:4096
	ds_read_u16 v204, v201 offset:128
	ds_read_b32 v208, v202 offset:4352
	ds_read_u16 v205, v201 offset:256
	ds_read_b32 v209, v202 offset:4608
	ds_read_u16 v206, v201 offset:384
	ds_read_b32 v210, v202 offset:4864
	ds_read_u16 v228, v201 offset:512
	ds_read_b32 v232, v202 offset:5120
	ds_read_u16 v229, v201 offset:640
	ds_read_b32 v233, v202 offset:5376
	ds_read_u16 v230, v201 offset:768
	ds_read_b32 v234, v202 offset:5632
	ds_read_u16 v231, v201 offset:896
	ds_read_b32 v235, v202 offset:5888
	s_waitcnt lgkmcnt(8)
	v_lshlrev_b32_e32 v212, 16, v203
	v_fmac_f32_e32 v212, v207, v211
	v_bfe_u32 v213, v212, 16, 1
	v_add3_u32 v214, v212, v213, s10
	ds_write_b16_d16_hi v201, v214 offset:0
	v_lshlrev_b32_e32 v211, 16, v204
	v_fmac_f32_e32 v211, v208, v212
	v_bfe_u32 v213, v211, 16, 1
	v_add3_u32 v215, v211, v213, s10
	ds_write_b16_d16_hi v201, v215 offset:128
	v_lshlrev_b32_e32 v212, 16, v205
	v_fmac_f32_e32 v212, v209, v211
	v_bfe_u32 v213, v212, 16, 1
	v_add3_u32 v216, v212, v213, s10
	ds_write_b16_d16_hi v201, v216 offset:256
	v_lshlrev_b32_e32 v211, 16, v206
	v_fmac_f32_e32 v211, v210, v212
	v_bfe_u32 v213, v211, 16, 1
	v_add3_u32 v217, v211, v213, s10
	ds_write_b16_d16_hi v201, v217 offset:384
	ds_read_u16 v203, v201 offset:1024
	ds_read_b32 v207, v202 offset:6144
	ds_read_u16 v204, v201 offset:1152
	ds_read_b32 v208, v202 offset:6400
	ds_read_u16 v205, v201 offset:1280
	ds_read_b32 v209, v202 offset:6656
	ds_read_u16 v206, v201 offset:1408
	ds_read_b32 v210, v202 offset:6912
	s_waitcnt lgkmcnt(12)
	v_lshlrev_b32_e32 v212, 16, v228
	v_fmac_f32_e32 v212, v232, v211
	v_bfe_u32 v213, v212, 16, 1
	v_add3_u32 v214, v212, v213, s10
	ds_write_b16_d16_hi v201, v214 offset:512
	v_lshlrev_b32_e32 v211, 16, v229
	v_fmac_f32_e32 v211, v233, v212
	v_bfe_u32 v213, v211, 16, 1
	v_add3_u32 v215, v211, v213, s10
	ds_write_b16_d16_hi v201, v215 offset:640
	v_lshlrev_b32_e32 v212, 16, v230
	v_fmac_f32_e32 v212, v234, v211
	v_bfe_u32 v213, v212, 16, 1
	v_add3_u32 v216, v212, v213, s10
	ds_write_b16_d16_hi v201, v216 offset:768
	v_lshlrev_b32_e32 v211, 16, v231
	v_fmac_f32_e32 v211, v235, v212
	v_bfe_u32 v213, v211, 16, 1
	v_add3_u32 v217, v211, v213, s10
	ds_write_b16_d16_hi v201, v217 offset:896
	ds_read_u16 v228, v201 offset:1536
	ds_read_b32 v232, v202 offset:7168
	ds_read_u16 v229, v201 offset:1664
	ds_read_b32 v233, v202 offset:7424
	ds_read_u16 v230, v201 offset:1792
	ds_read_b32 v234, v202 offset:7680
	ds_read_u16 v231, v201 offset:1920
	ds_read_b32 v235, v202 offset:7936
	s_waitcnt lgkmcnt(12)
	v_lshlrev_b32_e32 v212, 16, v203
	v_fmac_f32_e32 v212, v207, v211
	v_bfe_u32 v213, v212, 16, 1
	v_add3_u32 v214, v212, v213, s10
	ds_write_b16_d16_hi v201, v214 offset:1024
	v_lshlrev_b32_e32 v211, 16, v204
	v_fmac_f32_e32 v211, v208, v212
	v_bfe_u32 v213, v211, 16, 1
	v_add3_u32 v215, v211, v213, s10
	ds_write_b16_d16_hi v201, v215 offset:1152
	v_lshlrev_b32_e32 v212, 16, v205
	v_fmac_f32_e32 v212, v209, v211
	v_bfe_u32 v213, v212, 16, 1
	v_add3_u32 v216, v212, v213, s10
	ds_write_b16_d16_hi v201, v216 offset:1280
	v_lshlrev_b32_e32 v211, 16, v206
	v_fmac_f32_e32 v211, v210, v212
	v_bfe_u32 v213, v211, 16, 1
	v_add3_u32 v217, v211, v213, s10
	ds_write_b16_d16_hi v201, v217 offset:1408
	ds_read_u16 v203, v201 offset:2048
	ds_read_b32 v207, v202 offset:8192
	ds_read_u16 v204, v201 offset:2176
	ds_read_b32 v208, v202 offset:8448
	ds_read_u16 v205, v201 offset:2304
	ds_read_b32 v209, v202 offset:8704
	ds_read_u16 v206, v201 offset:2432
	ds_read_b32 v210, v202 offset:8960
	s_waitcnt lgkmcnt(12)
	v_lshlrev_b32_e32 v212, 16, v228
	v_fmac_f32_e32 v212, v232, v211
	v_bfe_u32 v213, v212, 16, 1
	v_add3_u32 v214, v212, v213, s10
	ds_write_b16_d16_hi v201, v214 offset:1536
	v_lshlrev_b32_e32 v211, 16, v229
	v_fmac_f32_e32 v211, v233, v212
	v_bfe_u32 v213, v211, 16, 1
	v_add3_u32 v215, v211, v213, s10
	ds_write_b16_d16_hi v201, v215 offset:1664
	v_lshlrev_b32_e32 v212, 16, v230
	v_fmac_f32_e32 v212, v234, v211
	v_bfe_u32 v213, v212, 16, 1
	v_add3_u32 v216, v212, v213, s10
	ds_write_b16_d16_hi v201, v216 offset:1792
	v_lshlrev_b32_e32 v211, 16, v231
	v_fmac_f32_e32 v211, v235, v212
	v_bfe_u32 v213, v211, 16, 1
	v_add3_u32 v217, v211, v213, s10
	ds_write_b16_d16_hi v201, v217 offset:1920
	ds_read_u16 v228, v201 offset:2560
	ds_read_b32 v232, v202 offset:9216
	ds_read_u16 v229, v201 offset:2688
	ds_read_b32 v233, v202 offset:9472
	ds_read_u16 v230, v201 offset:2816
	ds_read_b32 v234, v202 offset:9728
	ds_read_u16 v231, v201 offset:2944
	ds_read_b32 v235, v202 offset:9984
	s_waitcnt lgkmcnt(12)
	v_lshlrev_b32_e32 v212, 16, v203
	v_fmac_f32_e32 v212, v207, v211
	v_bfe_u32 v213, v212, 16, 1
	v_add3_u32 v214, v212, v213, s10
	ds_write_b16_d16_hi v201, v214 offset:2048
	v_lshlrev_b32_e32 v211, 16, v204
	v_fmac_f32_e32 v211, v208, v212
	v_bfe_u32 v213, v211, 16, 1
	v_add3_u32 v215, v211, v213, s10
	ds_write_b16_d16_hi v201, v215 offset:2176
	v_lshlrev_b32_e32 v212, 16, v205
	v_fmac_f32_e32 v212, v209, v211
	v_bfe_u32 v213, v212, 16, 1
	v_add3_u32 v216, v212, v213, s10
	ds_write_b16_d16_hi v201, v216 offset:2304
	v_lshlrev_b32_e32 v211, 16, v206
	v_fmac_f32_e32 v211, v210, v212
	v_bfe_u32 v213, v211, 16, 1
	v_add3_u32 v217, v211, v213, s10
	ds_write_b16_d16_hi v201, v217 offset:2432
	ds_read_u16 v203, v201 offset:3072
	ds_read_b32 v207, v202 offset:10240
	ds_read_u16 v204, v201 offset:3200
	ds_read_b32 v208, v202 offset:10496
	ds_read_u16 v205, v201 offset:3328
	ds_read_b32 v209, v202 offset:10752
	ds_read_u16 v206, v201 offset:3456
	ds_read_b32 v210, v202 offset:11008
	s_waitcnt lgkmcnt(12)
; __device__ __forceinline__ unsigned f2bf(float f) { unsigned u = __builtin_bit_cast(unsigned, f); return (u + 0x7fffu + ((u >> 16) & 1u)) >> 16; }
; __global__ void __launch_bounds__(NT, 2) hymba_fwd(Args args) {
;     ...
;             for (int cb = 0; cb < 128; cb += 32) {
;                 unsigned vn[32]; float dn[32];
;                 const int nb = cb + 32 < 128 ? cb + 32 : cb;
; #pragma unroll
;                 for (int j = 0; j < 32; ++j) { vn[j] = p[(size_t)(nb + j) * 65536]; dn[j] = dc[(nb + j) * 512]; }
; #pragma unroll
;                 for (int j = 0; j < 32; ++j) { run = dv[j] * run + bf2f((unsigned short)v[j]); v[j] = f2bf(run); }
; #pragma unroll
;                 for (int j = 0; j < 32; ++j) { p[(size_t)(cb + j) * 65536] = (bf16)v[j]; v[j] = vn[j]; dv[j] = dn[j]; }
	v_lshlrev_b32_e32 v212, 16, v228
	v_fmac_f32_e32 v212, v232, v211
	v_bfe_u32 v213, v212, 16, 1
	v_add3_u32 v214, v212, v213, s10
	ds_write_b16_d16_hi v201, v214 offset:2560
	v_lshlrev_b32_e32 v211, 16, v229
	v_fmac_f32_e32 v211, v233, v212
	v_bfe_u32 v213, v211, 16, 1
	v_add3_u32 v215, v211, v213, s10
	ds_write_b16_d16_hi v201, v215 offset:2688
	v_lshlrev_b32_e32 v212, 16, v230
	v_fmac_f32_e32 v212, v234, v211
	v_bfe_u32 v213, v212, 16, 1
	v_add3_u32 v216, v212, v213, s10
	ds_write_b16_d16_hi v201, v216 offset:2816
	v_lshlrev_b32_e32 v211, 16, v231
	v_fmac_f32_e32 v211, v235, v212
	v_bfe_u32 v213, v211, 16, 1
	v_add3_u32 v217, v211, v213, s10
	ds_write_b16_d16_hi v201, v217 offset:2944
	ds_read_u16 v228, v201 offset:3584
	ds_read_b32 v232, v202 offset:11264
	ds_read_u16 v229, v201 offset:3712
	ds_read_b32 v233, v202 offset:11520
	ds_read_u16 v230, v201 offset:3840
	ds_read_b32 v234, v202 offset:11776
	ds_read_u16 v231, v201 offset:3968
	ds_read_b32 v235, v202 offset:12032
	s_waitcnt lgkmcnt(12)
	v_lshlrev_b32_e32 v212, 16, v203
	v_fmac_f32_e32 v212, v207, v211
	v_bfe_u32 v213, v212, 16, 1
	v_add3_u32 v214, v212, v213, s10
	ds_write_b16_d16_hi v201, v214 offset:3072
	v_lshlrev_b32_e32 v211, 16, v204
	v_fmac_f32_e32 v211, v208, v212
	v_bfe_u32 v213, v211, 16, 1
	v_add3_u32 v215, v211, v213, s10
	ds_write_b16_d16_hi v201, v215 offset:3200
	v_lshlrev_b32_e32 v212, 16, v205
	v_fmac_f32_e32 v212, v209, v211
	v_bfe_u32 v213, v212, 16, 1
	v_add3_u32 v216, v212, v213, s10
	ds_write_b16_d16_hi v201, v216 offset:3328
	v_lshlrev_b32_e32 v211, 16, v206
	v_fmac_f32_e32 v211, v210, v212
	v_bfe_u32 v213, v211, 16, 1
	v_add3_u32 v217, v211, v213, s10
	ds_write_b16_d16_hi v201, v217 offset:3456
	s_waitcnt lgkmcnt(4)
	v_lshlrev_b32_e32 v212, 16, v228
	v_fmac_f32_e32 v212, v232, v211
	v_bfe_u32 v213, v212, 16, 1
	v_add3_u32 v214, v212, v213, s10
	ds_write_b16_d16_hi v201, v214 offset:3584
	v_lshlrev_b32_e32 v211, 16, v229
	v_fmac_f32_e32 v211, v233, v212
	v_bfe_u32 v213, v211, 16, 1
	v_add3_u32 v215, v211, v213, s10
	ds_write_b16_d16_hi v201, v215 offset:3712
	v_lshlrev_b32_e32 v212, 16, v230
	v_fmac_f32_e32 v212, v234, v211
	v_bfe_u32 v213, v212, 16, 1
	v_add3_u32 v216, v212, v213, s10
	ds_write_b16_d16_hi v201, v216 offset:3840
	v_lshlrev_b32_e32 v211, 16, v231
	v_fmac_f32_e32 v211, v235, v212
	v_bfe_u32 v213, v211, 16, 1
	v_add3_u32 v217, v211, v213, s10
	ds_write_b16_d16_hi v201, v217 offset:3968
	ds_read_b128 v[0:3], v200 offset:0
	ds_read_b128 v[4:7], v200 offset:1024
	ds_read_b128 v[8:11], v200 offset:2048
	ds_read_b128 v[12:15], v200 offset:3072
	s_waitcnt lgkmcnt(0)
	global_store_dwordx4 v198, v[0:3], s[12:13]
	s_add_u32 s12, s12, 0x100000
	s_addc_u32 s13, s13, 0
	global_store_dwordx4 v198, v[4:7], s[12:13]
	s_add_u32 s12, s12, 0x100000
	s_addc_u32 s13, s13, 0
	global_store_dwordx4 v198, v[8:11], s[12:13]
	s_add_u32 s12, s12, 0x100000
	s_addc_u32 s13, s13, 0
	global_store_dwordx4 v198, v[12:15], s[12:13]
	s_add_u32 s12, s12, 0x100000
	s_addc_u32 s13, s13, 0
	s_waitcnt vmcnt(28)
	ds_write_b128 v200, v[16:19] offset:0
	ds_write_b128 v200, v[20:23] offset:1024
	ds_write_b128 v200, v[24:27] offset:2048
	ds_write_b128 v200, v[28:31] offset:3072
	ds_write_b128 v200, v[96:99] offset:4096
	ds_write_b128 v200, v[100:103] offset:5120
	ds_write_b128 v200, v[104:107] offset:6144
	ds_write_b128 v200, v[108:111] offset:7168
	ds_write_b128 v200, v[112:115] offset:8192
	ds_write_b128 v200, v[116:119] offset:9216
	ds_write_b128 v200, v[120:123] offset:10240
	ds_write_b128 v200, v[124:127] offset:11264
	ds_read_u16 v203, v201 offset:0
	ds_read_b32 v207, v202 offset:4096
	ds_read_u16 v204, v201 offset:128
	ds_read_b32 v208, v202 offset:4352
	ds_read_u16 v205, v201 offset:256
	ds_read_b32 v209, v202 offset:4608
	ds_read_u16 v206, v201 offset:384
	ds_read_b32 v210, v202 offset:4864
	ds_read_u16 v228, v201 offset:512
	ds_read_b32 v232, v202 offset:5120
	ds_read_u16 v229, v201 offset:640
	ds_read_b32 v233, v202 offset:5376
	ds_read_u16 v230, v201 offset:768
	ds_read_b32 v234, v202 offset:5632
	ds_read_u16 v231, v201 offset:896
	ds_read_b32 v235, v202 offset:5888
	s_waitcnt lgkmcnt(8)
	v_lshlrev_b32_e32 v212, 16, v203
	v_fmac_f32_e32 v212, v207, v211
	v_bfe_u32 v213, v212, 16, 1
	v_add3_u32 v214, v212, v213, s10
	ds_write_b16_d16_hi v201, v214 offset:0
	v_lshlrev_b32_e32 v211, 16, v204
	v_fmac_f32_e32 v211, v208, v212
	v_bfe_u32 v213, v211, 16, 1
	v_add3_u32 v215, v211, v213, s10
	ds_write_b16_d16_hi v201, v215 offset:128
	v_lshlrev_b32_e32 v212, 16, v205
	v_fmac_f32_e32 v212, v209, v211
	v_bfe_u32 v213, v212, 16, 1
	v_add3_u32 v216, v212, v213, s10
	ds_write_b16_d16_hi v201, v216 offset:256
	v_lshlrev_b32_e32 v211, 16, v206
	v_fmac_f32_e32 v211, v210, v212
	v_bfe_u32 v213, v211, 16, 1
	v_add3_u32 v217, v211, v213, s10
	ds_write_b16_d16_hi v201, v217 offset:384
	ds_read_u16 v203, v201 offset:1024
	ds_read_b32 v207, v202 offset:6144
	ds_read_u16 v204, v201 offset:1152
	ds_read_b32 v208, v202 offset:6400
	ds_read_u16 v205, v201 offset:1280
	ds_read_b32 v209, v202 offset:6656
	ds_read_u16 v206, v201 offset:1408
	ds_read_b32 v210, v202 offset:6912
	s_waitcnt lgkmcnt(12)
	v_lshlrev_b32_e32 v212, 16, v228
	v_fmac_f32_e32 v212, v232, v211
	v_bfe_u32 v213, v212, 16, 1
	v_add3_u32 v214, v212, v213, s10
	ds_write_b16_d16_hi v201, v214 offset:512
	v_lshlrev_b32_e32 v211, 16, v229
	v_fmac_f32_e32 v211, v233, v212
	v_bfe_u32 v213, v211, 16, 1
	v_add3_u32 v215, v211, v213, s10
	ds_write_b16_d16_hi v201, v215 offset:640
	v_lshlrev_b32_e32 v212, 16, v230
	v_fmac_f32_e32 v212, v234, v211
	v_bfe_u32 v213, v212, 16, 1
	v_add3_u32 v216, v212, v213, s10
	ds_write_b16_d16_hi v201, v216 offset:768
	v_lshlrev_b32_e32 v211, 16, v231
	v_fmac_f32_e32 v211, v235, v212
	v_bfe_u32 v213, v211, 16, 1
	v_add3_u32 v217, v211, v213, s10
	ds_write_b16_d16_hi v201, v217 offset:896
	ds_read_u16 v228, v201 offset:1536
	ds_read_b32 v232, v202 offset:7168
	ds_read_u16 v229, v201 offset:1664
	ds_read_b32 v233, v202 offset:7424
	ds_read_u16 v230, v201 offset:1792
	ds_read_b32 v234, v202 offset:7680
	ds_read_u16 v231, v201 offset:1920
	ds_read_b32 v235, v202 offset:7936
	s_waitcnt lgkmcnt(12)
; __device__ __forceinline__ unsigned f2bf(float f) { unsigned u = __builtin_bit_cast(unsigned, f); return (u + 0x7fffu + ((u >> 16) & 1u)) >> 16; }
; __global__ void __launch_bounds__(NT, 2) hymba_fwd(Args args) {
;     ...
;             for (int cb = 0; cb < 128; cb += 32) {
;                 unsigned vn[32]; float dn[32];
;                 const int nb = cb + 32 < 128 ? cb + 32 : cb;
; #pragma unroll
;                 for (int j = 0; j < 32; ++j) { vn[j] = p[(size_t)(nb + j) * 65536]; dn[j] = dc[(nb + j) * 512]; }
; #pragma unroll
;                 for (int j = 0; j < 32; ++j) { run = dv[j] * run + bf2f((unsigned short)v[j]); v[j] = f2bf(run); }
; #pragma unroll
;                 for (int j = 0; j < 32; ++j) { p[(size_t)(cb + j) * 65536] = (bf16)v[j]; v[j] = vn[j]; dv[j] = dn[j]; }
	v_lshlrev_b32_e32 v212, 16, v203
	v_fmac_f32_e32 v212, v207, v211
	v_bfe_u32 v213, v212, 16, 1
	v_add3_u32 v214, v212, v213, s10
	ds_write_b16_d16_hi v201, v214 offset:1024
	v_lshlrev_b32_e32 v211, 16, v204
	v_fmac_f32_e32 v211, v208, v212
	v_bfe_u32 v213, v211, 16, 1
	v_add3_u32 v215, v211, v213, s10
	ds_write_b16_d16_hi v201, v215 offset:1152
	v_lshlrev_b32_e32 v212, 16, v205
	v_fmac_f32_e32 v212, v209, v211
	v_bfe_u32 v213, v212, 16, 1
	v_add3_u32 v216, v212, v213, s10
	ds_write_b16_d16_hi v201, v216 offset:1280
	v_lshlrev_b32_e32 v211, 16, v206
	v_fmac_f32_e32 v211, v210, v212
	v_bfe_u32 v213, v211, 16, 1
	v_add3_u32 v217, v211, v213, s10
	ds_write_b16_d16_hi v201, v217 offset:1408
	ds_read_u16 v203, v201 offset:2048
	ds_read_b32 v207, v202 offset:8192
	ds_read_u16 v204, v201 offset:2176
	ds_read_b32 v208, v202 offset:8448
	ds_read_u16 v205, v201 offset:2304
	ds_read_b32 v209, v202 offset:8704
	ds_read_u16 v206, v201 offset:2432
	ds_read_b32 v210, v202 offset:8960
	s_waitcnt lgkmcnt(12)
	v_lshlrev_b32_e32 v212, 16, v228
	v_fmac_f32_e32 v212, v232, v211
	v_bfe_u32 v213, v212, 16, 1
	v_add3_u32 v214, v212, v213, s10
	ds_write_b16_d16_hi v201, v214 offset:1536
	v_lshlrev_b32_e32 v211, 16, v229
	v_fmac_f32_e32 v211, v233, v212
	v_bfe_u32 v213, v211, 16, 1
	v_add3_u32 v215, v211, v213, s10
	ds_write_b16_d16_hi v201, v215 offset:1664
	v_lshlrev_b32_e32 v212, 16, v230
	v_fmac_f32_e32 v212, v234, v211
	v_bfe_u32 v213, v212, 16, 1
	v_add3_u32 v216, v212, v213, s10
	ds_write_b16_d16_hi v201, v216 offset:1792
	v_lshlrev_b32_e32 v211, 16, v231
	v_fmac_f32_e32 v211, v235, v212
	v_bfe_u32 v213, v211, 16, 1
	v_add3_u32 v217, v211, v213, s10
	ds_write_b16_d16_hi v201, v217 offset:1920
	ds_read_u16 v228, v201 offset:2560
	ds_read_b32 v232, v202 offset:9216
	ds_read_u16 v229, v201 offset:2688
	ds_read_b32 v233, v202 offset:9472
	ds_read_u16 v230, v201 offset:2816
	ds_read_b32 v234, v202 offset:9728
	ds_read_u16 v231, v201 offset:2944
	ds_read_b32 v235, v202 offset:9984
	s_waitcnt lgkmcnt(12)
	v_lshlrev_b32_e32 v212, 16, v203
	v_fmac_f32_e32 v212, v207, v211
	v_bfe_u32 v213, v212, 16, 1
	v_add3_u32 v214, v212, v213, s10
	ds_write_b16_d16_hi v201, v214 offset:2048
	v_lshlrev_b32_e32 v211, 16, v204
	v_fmac_f32_e32 v211, v208, v212
	v_bfe_u32 v213, v211, 16, 1
	v_add3_u32 v215, v211, v213, s10
	ds_write_b16_d16_hi v201, v215 offset:2176
	v_lshlrev_b32_e32 v212, 16, v205
	v_fmac_f32_e32 v212, v209, v211
	v_bfe_u32 v213, v212, 16, 1
	v_add3_u32 v216, v212, v213, s10
	ds_write_b16_d16_hi v201, v216 offset:2304
	v_lshlrev_b32_e32 v211, 16, v206
	v_fmac_f32_e32 v211, v210, v212
	v_bfe_u32 v213, v211, 16, 1
	v_add3_u32 v217, v211, v213, s10
	ds_write_b16_d16_hi v201, v217 offset:2432
	ds_read_u16 v203, v201 offset:3072
	ds_read_b32 v207, v202 offset:10240
	ds_read_u16 v204, v201 offset:3200
	ds_read_b32 v208, v202 offset:10496
	ds_read_u16 v205, v201 offset:3328
	ds_read_b32 v209, v202 offset:10752
	ds_read_u16 v206, v201 offset:3456
	ds_read_b32 v210, v202 offset:11008
	s_waitcnt lgkmcnt(12)
	v_lshlrev_b32_e32 v212, 16, v228
	v_fmac_f32_e32 v212, v232, v211
	v_bfe_u32 v213, v212, 16, 1
	v_add3_u32 v214, v212, v213, s10
	ds_write_b16_d16_hi v201, v214 offset:2560
	v_lshlrev_b32_e32 v211, 16, v229
	v_fmac_f32_e32 v211, v233, v212
	v_bfe_u32 v213, v211, 16, 1
	v_add3_u32 v215, v211, v213, s10
	ds_write_b16_d16_hi v201, v215 offset:2688
	v_lshlrev_b32_e32 v212, 16, v230
	v_fmac_f32_e32 v212, v234, v211
	v_bfe_u32 v213, v212, 16, 1
	v_add3_u32 v216, v212, v213, s10
	ds_write_b16_d16_hi v201, v216 offset:2816
	v_lshlrev_b32_e32 v211, 16, v231
	v_fmac_f32_e32 v211, v235, v212
	v_bfe_u32 v213, v211, 16, 1
	v_add3_u32 v217, v211, v213, s10
	ds_write_b16_d16_hi v201, v217 offset:2944
	ds_read_u16 v228, v201 offset:3584
	ds_read_b32 v232, v202 offset:11264
	ds_read_u16 v229, v201 offset:3712
	ds_read_b32 v233, v202 offset:11520
	ds_read_u16 v230, v201 offset:3840
	ds_read_b32 v234, v202 offset:11776
	ds_read_u16 v231, v201 offset:3968
	ds_read_b32 v235, v202 offset:12032
	s_waitcnt lgkmcnt(12)
	v_lshlrev_b32_e32 v212, 16, v203
	v_fmac_f32_e32 v212, v207, v211
	v_bfe_u32 v213, v212, 16, 1
	v_add3_u32 v214, v212, v213, s10
	ds_write_b16_d16_hi v201, v214 offset:3072
	v_lshlrev_b32_e32 v211, 16, v204
	v_fmac_f32_e32 v211, v208, v212
	v_bfe_u32 v213, v211, 16, 1
	v_add3_u32 v215, v211, v213, s10
	ds_write_b16_d16_hi v201, v215 offset:3200
	v_lshlrev_b32_e32 v212, 16, v205
	v_fmac_f32_e32 v212, v209, v211
	v_bfe_u32 v213, v212, 16, 1
	v_add3_u32 v216, v212, v213, s10
	ds_write_b16_d16_hi v201, v216 offset:3328
	v_lshlrev_b32_e32 v211, 16, v206
	v_fmac_f32_e32 v211, v210, v212
	v_bfe_u32 v213, v211, 16, 1
	v_add3_u32 v217, v211, v213, s10
	ds_write_b16_d16_hi v201, v217 offset:3456
	s_waitcnt lgkmcnt(4)
	v_lshlrev_b32_e32 v212, 16, v228
	v_fmac_f32_e32 v212, v232, v211
	v_bfe_u32 v213, v212, 16, 1
	v_add3_u32 v214, v212, v213, s10
	ds_write_b16_d16_hi v201, v214 offset:3584
	v_lshlrev_b32_e32 v211, 16, v229
	v_fmac_f32_e32 v211, v233, v212
	v_bfe_u32 v213, v211, 16, 1
	v_add3_u32 v215, v211, v213, s10
	ds_write_b16_d16_hi v201, v215 offset:3712
	v_lshlrev_b32_e32 v212, 16, v230
	v_fmac_f32_e32 v212, v234, v211
	v_bfe_u32 v213, v212, 16, 1
	v_add3_u32 v216, v212, v213, s10
	ds_write_b16_d16_hi v201, v216 offset:3840
	v_lshlrev_b32_e32 v211, 16, v231
	v_fmac_f32_e32 v211, v235, v212
	v_bfe_u32 v213, v211, 16, 1
	v_add3_u32 v217, v211, v213, s10
	ds_write_b16_d16_hi v201, v217 offset:3968
	ds_read_b128 v[16:19], v200 offset:0
	ds_read_b128 v[20:23], v200 offset:1024
	ds_read_b128 v[24:27], v200 offset:2048
	ds_read_b128 v[28:31], v200 offset:3072
	s_waitcnt lgkmcnt(0)
; __device__ __forceinline__ unsigned f2bf(float f) { unsigned u = __builtin_bit_cast(unsigned, f); return (u + 0x7fffu + ((u >> 16) & 1u)) >> 16; }
; __global__ void __launch_bounds__(NT, 2) hymba_fwd(Args args) {
;     ...
;             for (int cb = 0; cb < 128; cb += 32) {
;                 unsigned vn[32]; float dn[32];
;                 const int nb = cb + 32 < 128 ? cb + 32 : cb;
; #pragma unroll
;                 for (int j = 0; j < 32; ++j) { vn[j] = p[(size_t)(nb + j) * 65536]; dn[j] = dc[(nb + j) * 512]; }
; #pragma unroll
;                 for (int j = 0; j < 32; ++j) { run = dv[j] * run + bf2f((unsigned short)v[j]); v[j] = f2bf(run); }
; #pragma unroll
;                 for (int j = 0; j < 32; ++j) { p[(size_t)(cb + j) * 65536] = (bf16)v[j]; v[j] = vn[j]; dv[j] = dn[j]; }
	global_store_dwordx4 v198, v[16:19], s[12:13]
	s_add_u32 s12, s12, 0x100000
	s_addc_u32 s13, s13, 0
	global_store_dwordx4 v198, v[20:23], s[12:13]
	s_add_u32 s12, s12, 0x100000
	s_addc_u32 s13, s13, 0
	global_store_dwordx4 v198, v[24:27], s[12:13]
	s_add_u32 s12, s12, 0x100000
	s_addc_u32 s13, s13, 0
	global_store_dwordx4 v198, v[28:31], s[12:13]
	s_add_u32 s12, s12, 0x100000
	s_addc_u32 s13, s13, 0
	s_waitcnt vmcnt(20)
	ds_write_b128 v200, v[32:35] offset:0
	ds_write_b128 v200, v[36:39] offset:1024
	ds_write_b128 v200, v[40:43] offset:2048
	ds_write_b128 v200, v[44:47] offset:3072
	ds_write_b128 v200, v[128:131] offset:4096
	ds_write_b128 v200, v[132:135] offset:5120
	ds_write_b128 v200, v[136:139] offset:6144
	ds_write_b128 v200, v[140:143] offset:7168
	ds_write_b128 v200, v[144:147] offset:8192
	ds_write_b128 v200, v[148:151] offset:9216
	ds_write_b128 v200, v[152:155] offset:10240
	ds_write_b128 v200, v[156:159] offset:11264
	ds_read_u16 v203, v201 offset:0
	ds_read_b32 v207, v202 offset:4096
	ds_read_u16 v204, v201 offset:128
	ds_read_b32 v208, v202 offset:4352
	ds_read_u16 v205, v201 offset:256
	ds_read_b32 v209, v202 offset:4608
	ds_read_u16 v206, v201 offset:384
	ds_read_b32 v210, v202 offset:4864
	ds_read_u16 v228, v201 offset:512
	ds_read_b32 v232, v202 offset:5120
	ds_read_u16 v229, v201 offset:640
	ds_read_b32 v233, v202 offset:5376
	ds_read_u16 v230, v201 offset:768
	ds_read_b32 v234, v202 offset:5632
	ds_read_u16 v231, v201 offset:896
	ds_read_b32 v235, v202 offset:5888
	s_waitcnt lgkmcnt(8)
	v_lshlrev_b32_e32 v212, 16, v203
	v_fmac_f32_e32 v212, v207, v211
	v_bfe_u32 v213, v212, 16, 1
	v_add3_u32 v214, v212, v213, s10
	ds_write_b16_d16_hi v201, v214 offset:0
	v_lshlrev_b32_e32 v211, 16, v204
	v_fmac_f32_e32 v211, v208, v212
	v_bfe_u32 v213, v211, 16, 1
	v_add3_u32 v215, v211, v213, s10
	ds_write_b16_d16_hi v201, v215 offset:128
	v_lshlrev_b32_e32 v212, 16, v205
	v_fmac_f32_e32 v212, v209, v211
	v_bfe_u32 v213, v212, 16, 1
	v_add3_u32 v216, v212, v213, s10
	ds_write_b16_d16_hi v201, v216 offset:256
	v_lshlrev_b32_e32 v211, 16, v206
	v_fmac_f32_e32 v211, v210, v212
	v_bfe_u32 v213, v211, 16, 1
	v_add3_u32 v217, v211, v213, s10
	ds_write_b16_d16_hi v201, v217 offset:384
	ds_read_u16 v203, v201 offset:1024
	ds_read_b32 v207, v202 offset:6144
	ds_read_u16 v204, v201 offset:1152
	ds_read_b32 v208, v202 offset:6400
	ds_read_u16 v205, v201 offset:1280
	ds_read_b32 v209, v202 offset:6656
	ds_read_u16 v206, v201 offset:1408
	ds_read_b32 v210, v202 offset:6912
	s_waitcnt lgkmcnt(12)
	v_lshlrev_b32_e32 v212, 16, v228
	v_fmac_f32_e32 v212, v232, v211
	v_bfe_u32 v213, v212, 16, 1
	v_add3_u32 v214, v212, v213, s10
	ds_write_b16_d16_hi v201, v214 offset:512
	v_lshlrev_b32_e32 v211, 16, v229
	v_fmac_f32_e32 v211, v233, v212
	v_bfe_u32 v213, v211, 16, 1
	v_add3_u32 v215, v211, v213, s10
	ds_write_b16_d16_hi v201, v215 offset:640
	v_lshlrev_b32_e32 v212, 16, v230
	v_fmac_f32_e32 v212, v234, v211
	v_bfe_u32 v213, v212, 16, 1
	v_add3_u32 v216, v212, v213, s10
	ds_write_b16_d16_hi v201, v216 offset:768
	v_lshlrev_b32_e32 v211, 16, v231
	v_fmac_f32_e32 v211, v235, v212
	v_bfe_u32 v213, v211, 16, 1
	v_add3_u32 v217, v211, v213, s10
	ds_write_b16_d16_hi v201, v217 offset:896
	ds_read_u16 v228, v201 offset:1536
	ds_read_b32 v232, v202 offset:7168
	ds_read_u16 v229, v201 offset:1664
	ds_read_b32 v233, v202 offset:7424
	ds_read_u16 v230, v201 offset:1792
	ds_read_b32 v234, v202 offset:7680
	ds_read_u16 v231, v201 offset:1920
	ds_read_b32 v235, v202 offset:7936
	s_waitcnt lgkmcnt(12)
	v_lshlrev_b32_e32 v212, 16, v203
	v_fmac_f32_e32 v212, v207, v211
	v_bfe_u32 v213, v212, 16, 1
	v_add3_u32 v214, v212, v213, s10
	ds_write_b16_d16_hi v201, v214 offset:1024
	v_lshlrev_b32_e32 v211, 16, v204
	v_fmac_f32_e32 v211, v208, v212
	v_bfe_u32 v213, v211, 16, 1
	v_add3_u32 v215, v211, v213, s10
	ds_write_b16_d16_hi v201, v215 offset:1152
	v_lshlrev_b32_e32 v212, 16, v205
	v_fmac_f32_e32 v212, v209, v211
	v_bfe_u32 v213, v212, 16, 1
	v_add3_u32 v216, v212, v213, s10
	ds_write_b16_d16_hi v201, v216 offset:1280
	v_lshlrev_b32_e32 v211, 16, v206
	v_fmac_f32_e32 v211, v210, v212
	v_bfe_u32 v213, v211, 16, 1
	v_add3_u32 v217, v211, v213, s10
	ds_write_b16_d16_hi v201, v217 offset:1408
	ds_read_u16 v203, v201 offset:2048
	ds_read_b32 v207, v202 offset:8192
	ds_read_u16 v204, v201 offset:2176
	ds_read_b32 v208, v202 offset:8448
	ds_read_u16 v205, v201 offset:2304
	ds_read_b32 v209, v202 offset:8704
	ds_read_u16 v206, v201 offset:2432
	ds_read_b32 v210, v202 offset:8960
	s_waitcnt lgkmcnt(12)
	v_lshlrev_b32_e32 v212, 16, v228
	v_fmac_f32_e32 v212, v232, v211
	v_bfe_u32 v213, v212, 16, 1
	v_add3_u32 v214, v212, v213, s10
	ds_write_b16_d16_hi v201, v214 offset:1536
	v_lshlrev_b32_e32 v211, 16, v229
	v_fmac_f32_e32 v211, v233, v212
	v_bfe_u32 v213, v211, 16, 1
	v_add3_u32 v215, v211, v213, s10
	ds_write_b16_d16_hi v201, v215 offset:1664
	v_lshlrev_b32_e32 v212, 16, v230
	v_fmac_f32_e32 v212, v234, v211
	v_bfe_u32 v213, v212, 16, 1
	v_add3_u32 v216, v212, v213, s10
	ds_write_b16_d16_hi v201, v216 offset:1792
	v_lshlrev_b32_e32 v211, 16, v231
	v_fmac_f32_e32 v211, v235, v212
	v_bfe_u32 v213, v211, 16, 1
	v_add3_u32 v217, v211, v213, s10
	ds_write_b16_d16_hi v201, v217 offset:1920
	ds_read_u16 v228, v201 offset:2560
	ds_read_b32 v232, v202 offset:9216
	ds_read_u16 v229, v201 offset:2688
	ds_read_b32 v233, v202 offset:9472
	ds_read_u16 v230, v201 offset:2816
	ds_read_b32 v234, v202 offset:9728
	ds_read_u16 v231, v201 offset:2944
	ds_read_b32 v235, v202 offset:9984
	s_waitcnt lgkmcnt(12)
; __device__ __forceinline__ unsigned f2bf(float f) { unsigned u = __builtin_bit_cast(unsigned, f); return (u + 0x7fffu + ((u >> 16) & 1u)) >> 16; }
; __global__ void __launch_bounds__(NT, 2) hymba_fwd(Args args) {
;     ...
;             for (int cb = 0; cb < 128; cb += 32) {
;                 unsigned vn[32]; float dn[32];
;                 const int nb = cb + 32 < 128 ? cb + 32 : cb;
; #pragma unroll
;                 for (int j = 0; j < 32; ++j) { vn[j] = p[(size_t)(nb + j) * 65536]; dn[j] = dc[(nb + j) * 512]; }
; #pragma unroll
;                 for (int j = 0; j < 32; ++j) { run = dv[j] * run + bf2f((unsigned short)v[j]); v[j] = f2bf(run); }
; #pragma unroll
;                 for (int j = 0; j < 32; ++j) { p[(size_t)(cb + j) * 65536] = (bf16)v[j]; v[j] = vn[j]; dv[j] = dn[j]; }
	v_lshlrev_b32_e32 v212, 16, v203
	v_fmac_f32_e32 v212, v207, v211
	v_bfe_u32 v213, v212, 16, 1
	v_add3_u32 v214, v212, v213, s10
	ds_write_b16_d16_hi v201, v214 offset:2048
	v_lshlrev_b32_e32 v211, 16, v204
	v_fmac_f32_e32 v211, v208, v212
	v_bfe_u32 v213, v211, 16, 1
	v_add3_u32 v215, v211, v213, s10
	ds_write_b16_d16_hi v201, v215 offset:2176
	v_lshlrev_b32_e32 v212, 16, v205
	v_fmac_f32_e32 v212, v209, v211
	v_bfe_u32 v213, v212, 16, 1
	v_add3_u32 v216, v212, v213, s10
	ds_write_b16_d16_hi v201, v216 offset:2304
	v_lshlrev_b32_e32 v211, 16, v206
	v_fmac_f32_e32 v211, v210, v212
	v_bfe_u32 v213, v211, 16, 1
	v_add3_u32 v217, v211, v213, s10
	ds_write_b16_d16_hi v201, v217 offset:2432
	ds_read_u16 v203, v201 offset:3072
	ds_read_b32 v207, v202 offset:10240
	ds_read_u16 v204, v201 offset:3200
	ds_read_b32 v208, v202 offset:10496
	ds_read_u16 v205, v201 offset:3328
	ds_read_b32 v209, v202 offset:10752
	ds_read_u16 v206, v201 offset:3456
	ds_read_b32 v210, v202 offset:11008
	s_waitcnt lgkmcnt(12)
	v_lshlrev_b32_e32 v212, 16, v228
	v_fmac_f32_e32 v212, v232, v211
	v_bfe_u32 v213, v212, 16, 1
	v_add3_u32 v214, v212, v213, s10
	ds_write_b16_d16_hi v201, v214 offset:2560
	v_lshlrev_b32_e32 v211, 16, v229
	v_fmac_f32_e32 v211, v233, v212
	v_bfe_u32 v213, v211, 16, 1
	v_add3_u32 v215, v211, v213, s10
	ds_write_b16_d16_hi v201, v215 offset:2688
	v_lshlrev_b32_e32 v212, 16, v230
	v_fmac_f32_e32 v212, v234, v211
	v_bfe_u32 v213, v212, 16, 1
	v_add3_u32 v216, v212, v213, s10
	ds_write_b16_d16_hi v201, v216 offset:2816
	v_lshlrev_b32_e32 v211, 16, v231
	v_fmac_f32_e32 v211, v235, v212
	v_bfe_u32 v213, v211, 16, 1
	v_add3_u32 v217, v211, v213, s10
	ds_write_b16_d16_hi v201, v217 offset:2944
	ds_read_u16 v228, v201 offset:3584
	ds_read_b32 v232, v202 offset:11264
	ds_read_u16 v229, v201 offset:3712
	ds_read_b32 v233, v202 offset:11520
	ds_read_u16 v230, v201 offset:3840
	ds_read_b32 v234, v202 offset:11776
	ds_read_u16 v231, v201 offset:3968
	ds_read_b32 v235, v202 offset:12032
	s_waitcnt lgkmcnt(12)
	v_lshlrev_b32_e32 v212, 16, v203
	v_fmac_f32_e32 v212, v207, v211
	v_bfe_u32 v213, v212, 16, 1
	v_add3_u32 v214, v212, v213, s10
	ds_write_b16_d16_hi v201, v214 offset:3072
	v_lshlrev_b32_e32 v211, 16, v204
	v_fmac_f32_e32 v211, v208, v212
	v_bfe_u32 v213, v211, 16, 1
	v_add3_u32 v215, v211, v213, s10
	ds_write_b16_d16_hi v201, v215 offset:3200
	v_lshlrev_b32_e32 v212, 16, v205
	v_fmac_f32_e32 v212, v209, v211
	v_bfe_u32 v213, v212, 16, 1
	v_add3_u32 v216, v212, v213, s10
	ds_write_b16_d16_hi v201, v216 offset:3328
	v_lshlrev_b32_e32 v211, 16, v206
	v_fmac_f32_e32 v211, v210, v212
	v_bfe_u32 v213, v211, 16, 1
	v_add3_u32 v217, v211, v213, s10
	ds_write_b16_d16_hi v201, v217 offset:3456
	s_waitcnt lgkmcnt(4)
	v_lshlrev_b32_e32 v212, 16, v228
	v_fmac_f32_e32 v212, v232, v211
	v_bfe_u32 v213, v212, 16, 1
	v_add3_u32 v214, v212, v213, s10
	ds_write_b16_d16_hi v201, v214 offset:3584
	v_lshlrev_b32_e32 v211, 16, v229
	v_fmac_f32_e32 v211, v233, v212
	v_bfe_u32 v213, v211, 16, 1
	v_add3_u32 v215, v211, v213, s10
	ds_write_b16_d16_hi v201, v215 offset:3712
	v_lshlrev_b32_e32 v212, 16, v230
	v_fmac_f32_e32 v212, v234, v211
	v_bfe_u32 v213, v212, 16, 1
	v_add3_u32 v216, v212, v213, s10
	ds_write_b16_d16_hi v201, v216 offset:3840
	v_lshlrev_b32_e32 v211, 16, v231
	v_fmac_f32_e32 v211, v235, v212
	v_bfe_u32 v213, v211, 16, 1
	v_add3_u32 v217, v211, v213, s10
	ds_write_b16_d16_hi v201, v217 offset:3968
	ds_read_b128 v[32:35], v200 offset:0
	ds_read_b128 v[36:39], v200 offset:1024
	ds_read_b128 v[40:43], v200 offset:2048
	ds_read_b128 v[44:47], v200 offset:3072
	s_waitcnt lgkmcnt(0)
	global_store_dwordx4 v198, v[32:35], s[12:13]
	s_add_u32 s12, s12, 0x100000
	s_addc_u32 s13, s13, 0
	global_store_dwordx4 v198, v[36:39], s[12:13]
	s_add_u32 s12, s12, 0x100000
	s_addc_u32 s13, s13, 0
	global_store_dwordx4 v198, v[40:43], s[12:13]
	s_add_u32 s12, s12, 0x100000
	s_addc_u32 s13, s13, 0
	global_store_dwordx4 v198, v[44:47], s[12:13]
	s_add_u32 s12, s12, 0x100000
	s_addc_u32 s13, s13, 0
	s_waitcnt vmcnt(12)
	ds_write_b128 v200, v[48:51] offset:0
	ds_write_b128 v200, v[52:55] offset:1024
	ds_write_b128 v200, v[56:59] offset:2048
	ds_write_b128 v200, v[60:63] offset:3072
	ds_write_b128 v200, v[160:163] offset:4096
	ds_write_b128 v200, v[164:167] offset:5120
	ds_write_b128 v200, v[168:171] offset:6144
	ds_write_b128 v200, v[172:175] offset:7168
	ds_write_b128 v200, v[180:183] offset:8192
	ds_write_b128 v200, v[184:187] offset:9216
	ds_write_b128 v200, v[188:191] offset:10240
	ds_write_b128 v200, v[194:197] offset:11264
	ds_read_u16 v203, v201 offset:0
	ds_read_b32 v207, v202 offset:4096
	ds_read_u16 v204, v201 offset:128
	ds_read_b32 v208, v202 offset:4352
	ds_read_u16 v205, v201 offset:256
	ds_read_b32 v209, v202 offset:4608
	ds_read_u16 v206, v201 offset:384
	ds_read_b32 v210, v202 offset:4864
	ds_read_u16 v228, v201 offset:512
	ds_read_b32 v232, v202 offset:5120
	ds_read_u16 v229, v201 offset:640
	ds_read_b32 v233, v202 offset:5376
	ds_read_u16 v230, v201 offset:768
	ds_read_b32 v234, v202 offset:5632
	ds_read_u16 v231, v201 offset:896
	ds_read_b32 v235, v202 offset:5888
	s_waitcnt lgkmcnt(8)
; __device__ __forceinline__ unsigned f2bf(float f) { unsigned u = __builtin_bit_cast(unsigned, f); return (u + 0x7fffu + ((u >> 16) & 1u)) >> 16; }
; __global__ void __launch_bounds__(NT, 2) hymba_fwd(Args args) {
;     ...
;             for (int cb = 0; cb < 128; cb += 32) {
;                 unsigned vn[32]; float dn[32];
;                 const int nb = cb + 32 < 128 ? cb + 32 : cb;
; #pragma unroll
;                 for (int j = 0; j < 32; ++j) { vn[j] = p[(size_t)(nb + j) * 65536]; dn[j] = dc[(nb + j) * 512]; }
; #pragma unroll
;                 for (int j = 0; j < 32; ++j) { run = dv[j] * run + bf2f((unsigned short)v[j]); v[j] = f2bf(run); }
; #pragma unroll
;                 for (int j = 0; j < 32; ++j) { p[(size_t)(cb + j) * 65536] = (bf16)v[j]; v[j] = vn[j]; dv[j] = dn[j]; }
	v_lshlrev_b32_e32 v212, 16, v203
	v_fmac_f32_e32 v212, v207, v211
	v_bfe_u32 v213, v212, 16, 1
	v_add3_u32 v214, v212, v213, s10
	ds_write_b16_d16_hi v201, v214 offset:0
	v_lshlrev_b32_e32 v211, 16, v204
	v_fmac_f32_e32 v211, v208, v212
	v_bfe_u32 v213, v211, 16, 1
	v_add3_u32 v215, v211, v213, s10
	ds_write_b16_d16_hi v201, v215 offset:128
	v_lshlrev_b32_e32 v212, 16, v205
	v_fmac_f32_e32 v212, v209, v211
	v_bfe_u32 v213, v212, 16, 1
	v_add3_u32 v216, v212, v213, s10
	ds_write_b16_d16_hi v201, v216 offset:256
	v_lshlrev_b32_e32 v211, 16, v206
	v_fmac_f32_e32 v211, v210, v212
	v_bfe_u32 v213, v211, 16, 1
	v_add3_u32 v217, v211, v213, s10
	ds_write_b16_d16_hi v201, v217 offset:384
	ds_read_u16 v203, v201 offset:1024
	ds_read_b32 v207, v202 offset:6144
	ds_read_u16 v204, v201 offset:1152
	ds_read_b32 v208, v202 offset:6400
	ds_read_u16 v205, v201 offset:1280
	ds_read_b32 v209, v202 offset:6656
	ds_read_u16 v206, v201 offset:1408
	ds_read_b32 v210, v202 offset:6912
	s_waitcnt lgkmcnt(12)
	v_lshlrev_b32_e32 v212, 16, v228
	v_fmac_f32_e32 v212, v232, v211
	v_bfe_u32 v213, v212, 16, 1
	v_add3_u32 v214, v212, v213, s10
	ds_write_b16_d16_hi v201, v214 offset:512
	v_lshlrev_b32_e32 v211, 16, v229
	v_fmac_f32_e32 v211, v233, v212
	v_bfe_u32 v213, v211, 16, 1
	v_add3_u32 v215, v211, v213, s10
	ds_write_b16_d16_hi v201, v215 offset:640
	v_lshlrev_b32_e32 v212, 16, v230
	v_fmac_f32_e32 v212, v234, v211
	v_bfe_u32 v213, v212, 16, 1
	v_add3_u32 v216, v212, v213, s10
	ds_write_b16_d16_hi v201, v216 offset:768
	v_lshlrev_b32_e32 v211, 16, v231
	v_fmac_f32_e32 v211, v235, v212
	v_bfe_u32 v213, v211, 16, 1
	v_add3_u32 v217, v211, v213, s10
	ds_write_b16_d16_hi v201, v217 offset:896
	ds_read_u16 v228, v201 offset:1536
	ds_read_b32 v232, v202 offset:7168
	ds_read_u16 v229, v201 offset:1664
	ds_read_b32 v233, v202 offset:7424
	ds_read_u16 v230, v201 offset:1792
	ds_read_b32 v234, v202 offset:7680
	ds_read_u16 v231, v201 offset:1920
	ds_read_b32 v235, v202 offset:7936
	s_waitcnt lgkmcnt(12)
	v_lshlrev_b32_e32 v212, 16, v203
	v_fmac_f32_e32 v212, v207, v211
	v_bfe_u32 v213, v212, 16, 1
	v_add3_u32 v214, v212, v213, s10
	ds_write_b16_d16_hi v201, v214 offset:1024
	v_lshlrev_b32_e32 v211, 16, v204
	v_fmac_f32_e32 v211, v208, v212
	v_bfe_u32 v213, v211, 16, 1
	v_add3_u32 v215, v211, v213, s10
	ds_write_b16_d16_hi v201, v215 offset:1152
	v_lshlrev_b32_e32 v212, 16, v205
	v_fmac_f32_e32 v212, v209, v211
	v_bfe_u32 v213, v212, 16, 1
	v_add3_u32 v216, v212, v213, s10
	ds_write_b16_d16_hi v201, v216 offset:1280
	v_lshlrev_b32_e32 v211, 16, v206
	v_fmac_f32_e32 v211, v210, v212
	v_bfe_u32 v213, v211, 16, 1
	v_add3_u32 v217, v211, v213, s10
	ds_write_b16_d16_hi v201, v217 offset:1408
	ds_read_u16 v203, v201 offset:2048
	ds_read_b32 v207, v202 offset:8192
	ds_read_u16 v204, v201 offset:2176
	ds_read_b32 v208, v202 offset:8448
	ds_read_u16 v205, v201 offset:2304
	ds_read_b32 v209, v202 offset:8704
	ds_read_u16 v206, v201 offset:2432
	ds_read_b32 v210, v202 offset:8960
	s_waitcnt lgkmcnt(12)
	v_lshlrev_b32_e32 v212, 16, v228
	v_fmac_f32_e32 v212, v232, v211
	v_bfe_u32 v213, v212, 16, 1
	v_add3_u32 v214, v212, v213, s10
	ds_write_b16_d16_hi v201, v214 offset:1536
	v_lshlrev_b32_e32 v211, 16, v229
	v_fmac_f32_e32 v211, v233, v212
	v_bfe_u32 v213, v211, 16, 1
	v_add3_u32 v215, v211, v213, s10
	ds_write_b16_d16_hi v201, v215 offset:1664
	v_lshlrev_b32_e32 v212, 16, v230
	v_fmac_f32_e32 v212, v234, v211
	v_bfe_u32 v213, v212, 16, 1
	v_add3_u32 v216, v212, v213, s10
	ds_write_b16_d16_hi v201, v216 offset:1792
	v_lshlrev_b32_e32 v211, 16, v231
	v_fmac_f32_e32 v211, v235, v212
	v_bfe_u32 v213, v211, 16, 1
	v_add3_u32 v217, v211, v213, s10
	ds_write_b16_d16_hi v201, v217 offset:1920
	ds_read_u16 v228, v201 offset:2560
	ds_read_b32 v232, v202 offset:9216
	ds_read_u16 v229, v201 offset:2688
	ds_read_b32 v233, v202 offset:9472
	ds_read_u16 v230, v201 offset:2816
	ds_read_b32 v234, v202 offset:9728
	ds_read_u16 v231, v201 offset:2944
	ds_read_b32 v235, v202 offset:9984
	s_waitcnt lgkmcnt(12)
; __device__ __forceinline__ unsigned f2bf(float f) { unsigned u = __builtin_bit_cast(unsigned, f); return (u + 0x7fffu + ((u >> 16) & 1u)) >> 16; }
; __global__ void __launch_bounds__(NT, 2) hymba_fwd(Args args) {
;     ...
;             for (int cb = 0; cb < 128; cb += 32) {
;                 unsigned vn[32]; float dn[32];
;                 const int nb = cb + 32 < 128 ? cb + 32 : cb;
; #pragma unroll
;                 for (int j = 0; j < 32; ++j) { vn[j] = p[(size_t)(nb + j) * 65536]; dn[j] = dc[(nb + j) * 512]; }
; #pragma unroll
;                 for (int j = 0; j < 32; ++j) { run = dv[j] * run + bf2f((unsigned short)v[j]); v[j] = f2bf(run); }
; #pragma unroll
;                 for (int j = 0; j < 32; ++j) { p[(size_t)(cb + j) * 65536] = (bf16)v[j]; v[j] = vn[j]; dv[j] = dn[j]; }
;             } }
;         if (!(args.flags & 1)) { const int gw = bid * NWAVES + wave, NGW = G * NWAVES;
;             for (int sid = gw; sid < 4096; sid += NGW) { const int h = sid >> 9, qb = (sid >> 2) & 127, sub = sid & 3; sb_strip(SQ, SK, SV, OMIX, h, 128 + 128 * qb + 32 * sub, lane, lds + wave * 8192); } }
	v_lshlrev_b32_e32 v212, 16, v203
	v_fmac_f32_e32 v212, v207, v211
	v_bfe_u32 v213, v212, 16, 1
	v_add3_u32 v214, v212, v213, s10
	ds_write_b16_d16_hi v201, v214 offset:2048
	v_lshlrev_b32_e32 v211, 16, v204
	v_fmac_f32_e32 v211, v208, v212
	v_bfe_u32 v213, v211, 16, 1
	v_add3_u32 v215, v211, v213, s10
	ds_write_b16_d16_hi v201, v215 offset:2176
	v_lshlrev_b32_e32 v212, 16, v205
	v_fmac_f32_e32 v212, v209, v211
	v_bfe_u32 v213, v212, 16, 1
	v_add3_u32 v216, v212, v213, s10
	ds_write_b16_d16_hi v201, v216 offset:2304
	v_lshlrev_b32_e32 v211, 16, v206
	v_fmac_f32_e32 v211, v210, v212
	v_bfe_u32 v213, v211, 16, 1
	v_add3_u32 v217, v211, v213, s10
	ds_write_b16_d16_hi v201, v217 offset:2432
	ds_read_u16 v203, v201 offset:3072
	ds_read_b32 v207, v202 offset:10240
	ds_read_u16 v204, v201 offset:3200
	ds_read_b32 v208, v202 offset:10496
	ds_read_u16 v205, v201 offset:3328
	ds_read_b32 v209, v202 offset:10752
	ds_read_u16 v206, v201 offset:3456
	ds_read_b32 v210, v202 offset:11008
	s_waitcnt lgkmcnt(12)
	v_lshlrev_b32_e32 v212, 16, v228
	v_fmac_f32_e32 v212, v232, v211
	v_bfe_u32 v213, v212, 16, 1
	v_add3_u32 v214, v212, v213, s10
	ds_write_b16_d16_hi v201, v214 offset:2560
	v_lshlrev_b32_e32 v211, 16, v229
	v_fmac_f32_e32 v211, v233, v212
	v_bfe_u32 v213, v211, 16, 1
	v_add3_u32 v215, v211, v213, s10
	ds_write_b16_d16_hi v201, v215 offset:2688
	v_lshlrev_b32_e32 v212, 16, v230
	v_fmac_f32_e32 v212, v234, v211
	v_bfe_u32 v213, v212, 16, 1
	v_add3_u32 v216, v212, v213, s10
	ds_write_b16_d16_hi v201, v216 offset:2816
	v_lshlrev_b32_e32 v211, 16, v231
	v_fmac_f32_e32 v211, v235, v212
	v_bfe_u32 v213, v211, 16, 1
	v_add3_u32 v217, v211, v213, s10
	ds_write_b16_d16_hi v201, v217 offset:2944
	ds_read_u16 v228, v201 offset:3584
	ds_read_b32 v232, v202 offset:11264
	ds_read_u16 v229, v201 offset:3712
	ds_read_b32 v233, v202 offset:11520
	ds_read_u16 v230, v201 offset:3840
	ds_read_b32 v234, v202 offset:11776
	ds_read_u16 v231, v201 offset:3968
	ds_read_b32 v235, v202 offset:12032
	s_waitcnt lgkmcnt(12)
	v_lshlrev_b32_e32 v212, 16, v203
	v_fmac_f32_e32 v212, v207, v211
	v_bfe_u32 v213, v212, 16, 1
	v_add3_u32 v214, v212, v213, s10
	ds_write_b16_d16_hi v201, v214 offset:3072
	v_lshlrev_b32_e32 v211, 16, v204
	v_fmac_f32_e32 v211, v208, v212
	v_bfe_u32 v213, v211, 16, 1
	v_add3_u32 v215, v211, v213, s10
	ds_write_b16_d16_hi v201, v215 offset:3200
	v_lshlrev_b32_e32 v212, 16, v205
	v_fmac_f32_e32 v212, v209, v211
	v_bfe_u32 v213, v212, 16, 1
	v_add3_u32 v216, v212, v213, s10
	ds_write_b16_d16_hi v201, v216 offset:3328
	v_lshlrev_b32_e32 v211, 16, v206
	v_fmac_f32_e32 v211, v210, v212
	v_bfe_u32 v213, v211, 16, 1
	v_add3_u32 v217, v211, v213, s10
	ds_write_b16_d16_hi v201, v217 offset:3456
	s_waitcnt lgkmcnt(4)
	v_lshlrev_b32_e32 v212, 16, v228
	v_fmac_f32_e32 v212, v232, v211
	v_bfe_u32 v213, v212, 16, 1
	v_add3_u32 v214, v212, v213, s10
	ds_write_b16_d16_hi v201, v214 offset:3584
	v_lshlrev_b32_e32 v211, 16, v229
	v_fmac_f32_e32 v211, v233, v212
	v_bfe_u32 v213, v211, 16, 1
	v_add3_u32 v215, v211, v213, s10
	ds_write_b16_d16_hi v201, v215 offset:3712
	v_lshlrev_b32_e32 v212, 16, v230
	v_fmac_f32_e32 v212, v234, v211
	v_bfe_u32 v213, v212, 16, 1
	v_add3_u32 v216, v212, v213, s10
	ds_write_b16_d16_hi v201, v216 offset:3840
	v_lshlrev_b32_e32 v211, 16, v231
	v_fmac_f32_e32 v211, v235, v212
	v_bfe_u32 v213, v211, 16, 1
	v_add3_u32 v217, v211, v213, s10
	ds_write_b16_d16_hi v201, v217 offset:3968
	ds_read_b128 v[48:51], v200 offset:0
	ds_read_b128 v[52:55], v200 offset:1024
	ds_read_b128 v[56:59], v200 offset:2048
	ds_read_b128 v[60:63], v200 offset:3072
	s_waitcnt lgkmcnt(0)
	global_store_dwordx4 v198, v[48:51], s[12:13]
	s_add_u32 s12, s12, 0x100000
	s_addc_u32 s13, s13, 0
	global_store_dwordx4 v198, v[52:55], s[12:13]
	s_add_u32 s12, s12, 0x100000
	s_addc_u32 s13, s13, 0
	global_store_dwordx4 v198, v[56:59], s[12:13]
	s_add_u32 s12, s12, 0x100000
	s_addc_u32 s13, s13, 0
	global_store_dwordx4 v198, v[60:63], s[12:13]
	s_add_u32 s12, s12, 0x100000
	s_addc_u32 s13, s13, 0
	s_setprio 1

; __global__ void __launch_bounds__(NT, 2) hymba_fwd(Args args) {
;     ...
;             for (int sid = gw; sid < 4096; sid += NGW) { const int h = sid >> 9, qb = (sid >> 2) & 127, sub = sid & 3; sb_strip(SQ, SK, SV, OMIX, h, 128 + 128 * qb + 32 * sub, lane, lds + wave * 8192); } }
;         __syncthreads();
.LBB0_1062:
	s_setprio 0
	s_waitcnt lgkmcnt(0)
	s_barrier
